# v32 + same per-row-group column-tile rotation in the FFN-in GEMM phases (P2, P10): XCDs work on different weight tiles at a time
# speedup vs baseline: 1.0140x; 1.0031x over previous
.LBB0_227:
	s_cmp_lt_i32 s76, 3
	s_cselect_b64 s[0:1], -1, 0
	s_add_u32 s80, s74, 0x5800000
	s_addc_u32 s81, s75, 0
	s_and_b64 s[0:1], s[0:1], s[2:3]
	s_andn2_b64 vcc, exec, s[0:1]
	s_cbranch_vccnz .LBB0_249
	s_cmpk_gt_i32 s96, 0x5d7
	v_readfirstlane_b32 s3, v236
	s_cbranch_scc1 .LBB0_244
	v_lshrrev_b32_e32 v0, 5, v236
	v_lshrrev_b32_e32 v2, 1, v236
	v_and_b32_e32 v0, 4, v0
	v_bfe_u32 v1, v236, 2, 2
	v_and_b32_e32 v11, 24, v2
	v_or3_b32 v0, v0, v1, v11
	v_lshlrev_b32_e32 v1, 4, v236
	v_add_u32_e32 v8, 0x2000, v1
	v_lshrrev_b32_e32 v2, 7, v8
	s_movk_i32 s2, 0xe0
	v_and_b32_e32 v4, 32, v236
	v_and_or_b32 v3, v2, s2, v0
	v_bitop3_b32 v9, v1, v4, 48 bitop3:0x6c
	v_and_b32_e32 v10, 64, v236
	v_bfe_u32 v12, v236, 2, 4
	s_movk_i32 s2, 0xf0
	v_or_b32_e32 v1, v9, v10
	v_and_or_b32 v2, v2, s2, v12
	s_add_u32 s26, s74, 0x100000
	v_lshl_or_b32 v130, v2, 11, v1
	v_lshrrev_b32_e32 v2, 3, v236
	s_movk_i32 s2, 0x60
	s_addc_u32 s27, s75, 0
	v_and_or_b32 v0, v2, s2, v0
	s_movk_i32 s2, 0x70
	s_ashr_i32 s29, s96, 31
	v_lshl_or_b32 v132, v0, 11, v1
	v_and_or_b32 v0, v2, s2, v12
	s_lshr_b32 s2, s29, 29
	s_add_i32 s2, s96, s2
	s_lshr_b32 s6, s3, 6
	s_ashr_i32 s4, s2, 3
	s_and_b32 s2, s2, -8
	s_lshr_b32 s8, s3, 8
	s_lshl_b32 s28, s6, 10
	s_sub_i32 s2, s96, s2
	s_cmp_lt_i32 s2, 0
	s_movk_i32 s30, 0xbc
	s_cselect_b32 s5, s30, 0xbb
	s_mul_i32 s2, s2, s5
	s_add_i32 s2, s2, s4
	s_mul_hi_i32 s4, s2, 0x2e8ba2e9
	s_lshr_b32 s5, s4, 31
	s_ashr_i32 s4, s4, 5
	s_add_i32 s4, s4, s5
	s_lshl_b32 s7, s4, 3
	s_sub_i32 s5, 0x44, s7
	s_mulk_i32 s4, 0xb0
	s_min_u32 s9, s5, 8
	s_sub_i32 s10, s2, s4
	v_lshl_or_b32 v128, v3, 11, v1
	s_sext_i32_i16 s2, s10
	v_cvt_f32_ubyte0_e32 v3, s9
	v_cvt_f32_i32_e32 v2, s2
	v_rcp_iflag_f32_e32 v4, v3
	v_lshl_or_b32 v134, v0, 11, v1
	s_ashr_i32 s2, s2, 30
	s_or_b32 s2, s2, 1
	v_mul_f32_e32 v0, v2, v4
	v_trunc_f32_e32 v0, v0
	v_fma_f32 v1, -v0, v3, v2
	v_cvt_i32_f32_e32 v0, v0
	v_cmp_ge_f32_e64 s[4:5], |v1|, v3
	s_and_b64 s[4:5], s[4:5], exec
	s_cselect_b32 s2, s2, 0
	v_readfirstlane_b32 s4, v0
	s_add_i32 s2, s4, s2
	s_mul_i32 s4, s2, s9
	s_sub_i32 s4, s10, s4
	s_sext_i32_i16 s4, s4
	s_add_i32 s18, s7, s4
	s_lshr_b32 s4, s18, 3
	s_mul_i32 s4, s4, 11
	s_lshr_b32 s4, s4, 3
	s_add_i32 s2, s2, s4
	s_cmp_gt_i32 s2, 21
	s_cselect_b32 s4, 22, 0
	s_sub_i32 s2, s2, s4
	s_ashr_i32 s19, s18, 31
	s_bfe_i64 s[10:11], s[2:3], 0x100000
	s_lshl_b64 s[4:5], s[18:19], 19
	s_lshl_b64 s[10:11], s[10:11], 19
	s_add_u32 s22, s26, s10
	s_addc_u32 s23, s27, s11
	s_add_i32 s19, s28, 0
	s_add_i32 m0, s19, 0x10000
	v_mov_b32_e32 v133, 0
	global_load_lds_dwordx4 v132, s[22:23]
	s_add_i32 m0, s19, 0x12000
	s_add_u32 s10, s22, 0x40000
	global_load_lds_dwordx4 v128, s[22:23]
	s_addc_u32 s11, s23, 0
	s_add_i32 m0, s19, 0x14000
	v_mov_b32_e32 v129, v133
	global_load_lds_dwordx4 v132, s[10:11]
	s_add_i32 m0, s19, 0x16000
	v_mov_b32_e32 v135, v133
	global_load_lds_dwordx4 v128, s[10:11]
	v_readlane_b32 s10, v246, 42
	v_readlane_b32 s11, v246, 43
	s_add_u32 s20, s10, s4
	s_addc_u32 s21, s11, s5
	s_add_i32 s31, s19, 0x2000
	s_mov_b32 m0, s19
	s_add_u32 s4, s20, 0x40000
	global_load_lds_dwordx4 v134, s[20:21]
	s_mov_b32 m0, s31
	s_addc_u32 s5, s21, 0
	s_add_i32 s33, s19, 0x4000
	global_load_lds_dwordx4 v130, s[20:21]
	s_mov_b32 m0, s33
	s_add_i32 s34, s19, 0x6000
	global_load_lds_dwordx4 v134, s[4:5]
	s_mov_b32 m0, s34
	v_mov_b32_e32 v131, v133
	global_load_lds_dwordx4 v130, s[4:5]
	s_cmp_eq_u32 s8, 1
	s_mov_b32 s35, 0
	v_lshl_add_u64 v[6:7], s[22:23], 0, v[132:133]
	v_lshl_add_u64 v[4:5], s[22:23], 0, v[128:129]
	v_lshl_add_u64 v[0:1], s[20:21], 0, v[134:135]
	s_cselect_b64 s[4:5], -1, 0
	s_cmp_lg_u32 s8, 1
	v_lshl_add_u64 v[2:3], s[20:21], 0, v[130:131]
	s_cbranch_scc1 .LBB0_231
	s_barrier

.LBB0_234:
	s_add_i32 s35, s35, 1
	s_mul_i32 s2, s35, s38
	s_mul_hi_u32 s3, s35, s39
	s_add_i32 s3, s3, s2
	s_mul_i32 s2, s35, s39
	s_add_u32 s14, s2, s96
	s_addc_u32 s15, s3, s29
	v_cmp_gt_i64_e32 vcc, s[14:15], v[142:143]
	v_cmp_lt_i64_e64 s[2:3], s[14:15], v[140:141]
	s_cbranch_vccnz .LBB0_236
	s_ashr_i32 s10, s14, 31
	s_lshr_b32 s10, s10, 29
	s_add_i32 s10, s14, s10
	s_ashr_i32 s11, s10, 3
	s_and_b32 s10, s10, -8
	s_sub_i32 s10, s14, s10
	s_cmp_lt_i32 s10, 0
	s_cselect_b32 s12, s30, 0xbb
	s_mul_i32 s10, s10, s12
	s_add_i32 s10, s10, s11
	s_mul_hi_i32 s11, s10, 0x2e8ba2e9
	s_lshr_b32 s12, s11, 31
	s_ashr_i32 s11, s11, 5
	s_add_i32 s11, s11, s12
	s_lshl_b32 s12, s11, 3
	s_sub_i32 s13, 0x44, s12
	s_min_i32 s13, s13, 8
	s_abs_i32 s14, s13
	v_cvt_f32_u32_e32 v0, s14
	s_sub_i32 s16, 0, s14
	s_mulk_i32 s11, 0xb0
	s_sub_i32 s11, s10, s11
	v_rcp_iflag_f32_e32 v0, v0
	s_abs_i32 s10, s11
	s_xor_b32 s15, s11, s13
	s_ashr_i32 s15, s15, 31
	v_mul_f32_e32 v0, 0x4f7ffffe, v0
	v_cvt_u32_f32_e32 v0, v0
	s_nop 0
	v_readfirstlane_b32 s17, v0
	s_mul_i32 s16, s16, s17
	s_mul_hi_u32 s16, s17, s16
	s_add_i32 s17, s17, s16
	s_mul_hi_u32 s16, s10, s17
	s_mul_i32 s17, s16, s14
	s_sub_i32 s10, s10, s17
	s_add_i32 s24, s16, 1
	s_sub_i32 s17, s10, s14
	s_cmp_ge_u32 s10, s14
	s_cselect_b32 s16, s24, s16
	s_cselect_b32 s10, s17, s10
	s_add_i32 s17, s16, 1
	s_cmp_ge_u32 s10, s14
	s_cselect_b32 s10, s17, s16
	s_xor_b32 s10, s10, s15
	s_sub_i32 s10, s10, s15
	s_mul_i32 s13, s10, s13
	s_sub_i32 s11, s11, s13
	s_add_i32 s12, s12, s11
	s_lshr_b32 s11, s12, 3
	s_mul_i32 s11, s11, 11
	s_lshr_b32 s11, s11, 3
	s_add_i32 s10, s10, s11
	s_cmp_gt_i32 s10, 21
	s_cselect_b32 s11, 22, 0
	s_sub_i32 s10, s10, s11

.LBB0_1209:
	s_cmp_lt_i32 s76, 11
	s_cselect_b64 s[2:3], -1, 0
	s_and_b64 s[0:1], s[2:3], s[0:1]
	s_andn2_b64 vcc, exec, s[0:1]
	s_cbranch_vccnz .LBB0_1243
	s_add_u32 s4, s74, 0x2500000
	s_addc_u32 s5, s75, 0
	v_readlane_b32 s9, v246, 46
	s_cmpk_gt_i32 s9, 0x5d7
	v_readfirstlane_b32 s3, v236
	s_cbranch_scc1 .LBB0_1226
	v_lshrrev_b32_e32 v0, 5, v236
	v_lshrrev_b32_e32 v2, 1, v236
	v_and_b32_e32 v0, 4, v0
	v_bfe_u32 v1, v236, 2, 2
	v_and_b32_e32 v11, 24, v2
	v_or3_b32 v0, v0, v1, v11
	v_lshlrev_b32_e32 v1, 4, v236
	v_add_u32_e32 v8, 0x2000, v1
	v_lshrrev_b32_e32 v2, 7, v8
	s_movk_i32 s2, 0xe0
	v_and_b32_e32 v4, 32, v236
	v_and_or_b32 v3, v2, s2, v0
	v_bitop3_b32 v9, v1, v4, 48 bitop3:0x6c
	v_and_b32_e32 v10, 64, v236
	v_bfe_u32 v12, v236, 2, 4
	s_movk_i32 s2, 0xf0
	v_or_b32_e32 v1, v9, v10
	v_and_or_b32 v2, v2, s2, v12
	v_lshl_or_b32 v130, v2, 11, v1
	v_lshrrev_b32_e32 v2, 3, v236
	s_movk_i32 s2, 0x60
	v_and_or_b32 v0, v2, s2, v0
	s_movk_i32 s2, 0x70
	s_ashr_i32 s29, s9, 31
	v_lshl_or_b32 v132, v0, 11, v1
	v_and_or_b32 v0, v2, s2, v12
	s_lshr_b32 s2, s29, 29
	s_add_i32 s2, s9, s2
	s_lshr_b32 s8, s3, 6
	s_ashr_i32 s6, s2, 3
	s_and_b32 s2, s2, -8
	s_lshr_b32 s10, s3, 8
	s_lshl_b32 s28, s8, 10
	s_sub_i32 s2, s9, s2
	s_cmp_lt_i32 s2, 0
	s_movk_i32 s30, 0xbc
	s_cselect_b32 s7, s30, 0xbb
	s_mul_i32 s2, s2, s7
	s_add_i32 s2, s2, s6
	s_mul_hi_i32 s6, s2, 0x2e8ba2e9
	s_lshr_b32 s7, s6, 31
	s_ashr_i32 s6, s6, 5
	s_add_i32 s6, s6, s7
	s_lshl_b32 s9, s6, 3
	s_sub_i32 s7, 0x44, s9
	s_mulk_i32 s6, 0xb0
	s_min_u32 s11, s7, 8
	s_sub_i32 s12, s2, s6
	v_lshl_or_b32 v128, v3, 11, v1
	s_sext_i32_i16 s2, s12
	v_cvt_f32_ubyte0_e32 v3, s11
	v_cvt_f32_i32_e32 v2, s2
	v_rcp_iflag_f32_e32 v4, v3
	v_lshl_or_b32 v134, v0, 11, v1
	s_ashr_i32 s2, s2, 30
	s_or_b32 s2, s2, 1
	v_mul_f32_e32 v0, v2, v4
	v_trunc_f32_e32 v0, v0
	v_fma_f32 v1, -v0, v3, v2
	v_cvt_i32_f32_e32 v0, v0
	v_cmp_ge_f32_e64 s[6:7], |v1|, v3
	s_and_b64 s[6:7], s[6:7], exec
	s_cselect_b32 s2, s2, 0
	v_readfirstlane_b32 s6, v0
	s_add_i32 s2, s6, s2
	s_mul_i32 s6, s2, s11
	s_sub_i32 s6, s12, s6
	s_sext_i32_i16 s6, s6
	s_add_i32 s20, s9, s6
	s_lshr_b32 s6, s20, 3
	s_mul_i32 s6, s6, 11
	s_lshr_b32 s6, s6, 3
	s_add_i32 s2, s2, s6
	s_cmp_gt_i32 s2, 21
	s_cselect_b32 s6, 22, 0
	s_sub_i32 s2, s2, s6
	s_ashr_i32 s21, s20, 31
	s_bfe_i64 s[12:13], s[2:3], 0x100000
	s_lshl_b64 s[6:7], s[20:21], 19
	s_lshl_b64 s[12:13], s[12:13], 19
	s_add_u32 s24, s4, s12
	s_addc_u32 s25, s5, s13
	s_add_i32 s21, s28, 0
	s_add_i32 m0, s21, 0x10000
	v_mov_b32_e32 v133, 0
	global_load_lds_dwordx4 v132, s[24:25]
	s_add_i32 m0, s21, 0x12000
	s_add_u32 s12, s24, 0x40000
	global_load_lds_dwordx4 v128, s[24:25]
	s_addc_u32 s13, s25, 0
	s_add_i32 m0, s21, 0x14000
	v_mov_b32_e32 v129, v133
	global_load_lds_dwordx4 v132, s[12:13]
	s_add_i32 m0, s21, 0x16000
	s_add_u32 s22, s92, s6
	s_addc_u32 s23, s93, s7
	s_add_i32 s31, s21, 0x2000
	global_load_lds_dwordx4 v128, s[12:13]
	s_mov_b32 m0, s21
	s_add_u32 s6, s22, 0x40000
	global_load_lds_dwordx4 v134, s[22:23]
	s_mov_b32 m0, s31
	s_addc_u32 s7, s23, 0
	s_add_i32 s33, s21, 0x4000
	global_load_lds_dwordx4 v130, s[22:23]
	s_mov_b32 m0, s33
	s_add_i32 s34, s21, 0x6000
	global_load_lds_dwordx4 v134, s[6:7]
	s_mov_b32 m0, s34
	v_mov_b32_e32 v135, v133
	global_load_lds_dwordx4 v130, s[6:7]
	v_mov_b32_e32 v131, v133
	s_cmp_eq_u32 s10, 1
	s_mov_b32 s35, 0
	v_lshl_add_u64 v[6:7], s[24:25], 0, v[132:133]
	v_lshl_add_u64 v[4:5], s[24:25], 0, v[128:129]
	v_lshl_add_u64 v[0:1], s[22:23], 0, v[134:135]
	s_cselect_b64 s[6:7], -1, 0
	s_cmp_lg_u32 s10, 1
	v_lshl_add_u64 v[2:3], s[22:23], 0, v[130:131]
	s_cbranch_scc1 .LBB0_1213
	s_barrier

.LBB0_1216:
	s_add_i32 s35, s35, 1
	s_mul_i32 s2, s35, s38
	s_mul_hi_u32 s3, s35, s39
	s_add_i32 s3, s3, s2
	s_mul_i32 s2, s35, s39
	v_readlane_b32 s13, v246, 46
	s_add_u32 s16, s2, s13
	s_addc_u32 s17, s3, s29
	v_cmp_gt_i64_e32 vcc, s[16:17], v[142:143]
	v_cmp_lt_i64_e64 s[2:3], s[16:17], v[140:141]
	s_cbranch_vccnz .LBB0_1218
	s_ashr_i32 s12, s16, 31
	s_lshr_b32 s12, s12, 29
	s_add_i32 s12, s16, s12
	s_ashr_i32 s13, s12, 3
	s_and_b32 s12, s12, -8
	s_sub_i32 s12, s16, s12
	s_cmp_lt_i32 s12, 0
	s_cselect_b32 s14, s30, 0xbb
	s_mul_i32 s12, s12, s14
	s_add_i32 s12, s12, s13
	s_mul_hi_i32 s13, s12, 0x2e8ba2e9
	s_lshr_b32 s14, s13, 31
	s_ashr_i32 s13, s13, 5
	s_add_i32 s13, s13, s14
	s_lshl_b32 s14, s13, 3
	s_sub_i32 s15, 0x44, s14
	s_min_i32 s15, s15, 8
	s_abs_i32 s16, s15
	v_cvt_f32_u32_e32 v0, s16
	s_sub_i32 s18, 0, s16
	s_mulk_i32 s13, 0xb0
	s_sub_i32 s13, s12, s13
	v_rcp_iflag_f32_e32 v0, v0
	s_abs_i32 s12, s13
	s_xor_b32 s17, s13, s15
	s_ashr_i32 s17, s17, 31
	v_mul_f32_e32 v0, 0x4f7ffffe, v0
	v_cvt_u32_f32_e32 v0, v0
	s_nop 0
	v_readfirstlane_b32 s19, v0
	s_mul_i32 s18, s18, s19
	s_mul_hi_u32 s18, s19, s18
	s_add_i32 s19, s19, s18
	s_mul_hi_u32 s18, s12, s19
	s_mul_i32 s19, s18, s16
	s_sub_i32 s12, s12, s19
	s_add_i32 s26, s18, 1
	s_sub_i32 s19, s12, s16
	s_cmp_ge_u32 s12, s16
	s_cselect_b32 s18, s26, s18
	s_cselect_b32 s12, s19, s12
	s_add_i32 s19, s18, 1
	s_cmp_ge_u32 s12, s16
	s_cselect_b32 s12, s19, s18
	s_xor_b32 s12, s12, s17
	s_sub_i32 s12, s12, s17
	s_mul_i32 s15, s12, s15
	s_sub_i32 s13, s13, s15
	s_add_i32 s14, s14, s13
	s_lshr_b32 s13, s14, 3
	s_mul_i32 s13, s13, 11
	s_lshr_b32 s13, s13, 3
	s_add_i32 s12, s12, s13
	s_cmp_gt_i32 s12, 21
	s_cselect_b32 s13, 22, 0
	s_sub_i32 s12, s12, s13
